# C loop as v2 plus a second (redundant) s_barrier per tile to test wave phase-locking
# speedup vs baseline: 1.0233x; 1.0141x over previous
; DI float ex2(float x) { return __builtin_amdgcn_exp2f(x); }
; #define MFMA32(a, b, c) __builtin_amdgcn_mfma_f32_32x32x16_bf16((a), (b), (c), 0, 0, 0)
; template <int MODE>
; DI void attn_unit(unsigned char* lds, const AttnParams& ap, int b, int h, int qb, int tid) {
;     ...
;     if (MODE == 1) {
; #pragma unroll
;       for (int kh = 0; kh < 2; ++kh) {
;         const bf16_t* kb = Ks + (32 * kh + r32) * 72 + 8 * hi;
;         bf16x8 p0[2], p1[2];
;         { f32x16 s0 = splat16(ap.negM);
;           s0 = MFMA32(*(const bf16x8*)(kb), qf[0], s0); s0 = MFMA32(*(const bf16x8*)(kb + 16), qf[1], s0);
; #pragma unroll
;           for (int i = 0; i < 16; ++i) { s0[i] = ex2(s0[i]); l0 += s0[i]; }
;           p0[0] = pack8(s0, 0); p0[1] = pack8(s0, 1); }
;         { f32x16 s1 = splat16(ap.negM);
;           s1 = MFMA32(*(const bf16x8*)(kb + 32), qf[2], s1); s1 = MFMA32(*(const bf16x8*)(kb + 48), qf[3], s1);
; #pragma unroll
;           for (int i = 0; i < 16; ++i) { s1[i] = ex2(s1[i]); l1 += s1[i]; }
;           p1[0] = pack8(s1, 0); p1[1] = pack8(s1, 1); }
; #pragma unroll
;         for (int kk = 0; kk < 2; ++kk) {
; #pragma unroll
;           for (int eb = 0; eb < 2; ++eb) { const bf16_t* vb = Vs + (32 * eb + r32) * 72 + 32 * kh + 16 * kk + 8 * hi; const bf16x8 vf = *(const bf16x8*)vb;
;             O0[eb] = MFMA32(vf, p0[kk], O0[eb]); O1[eb] = MFMA32(vf, p1[kk], O1[eb]); } }
.Lc_tile_loop:
	global_load_dwordx4 v[204:207], v[138:139], off
	global_load_dwordx4 v[142:145], v[136:137], off
	v_lshl_add_u64 v[138:139], v[138:139], 0, s[2:3]
	v_lshl_add_u64 v[136:137], v[136:137], 0, s[18:19]
	s_waitcnt lgkmcnt(0)
	v_mfma_f32_32x32x16_bf16 v[116:131], v[166:169], v[38:41], v[48:63]
	v_exp_f32_e32 v96, v96
	v_exp_f32_e32 v97, v97
	v_exp_f32_e32 v98, v98
	v_exp_f32_e32 v99, v99
	v_mfma_f32_32x32x16_bf16 v[116:131], v[170:173], v[34:37], v[116:131]
	v_exp_f32_e32 v100, v100
	v_exp_f32_e32 v101, v101
	v_exp_f32_e32 v102, v102
	v_exp_f32_e32 v103, v103
	ds_read_b128 v[166:169], v32 offset:4608
	ds_read_b128 v[170:173], v32 offset:4640
	v_mfma_f32_32x32x16_bf16 v[80:95], v[174:177], v[158:161], v[80:95]
	v_exp_f32_e32 v104, v104
	v_exp_f32_e32 v105, v105
	v_add_f32_e32 v141, v141, v96
	v_add_f32_e32 v150, v150, v97
	v_add_f32_e32 v141, v141, v98
	v_add_f32_e32 v150, v150, v99
	v_mfma_f32_32x32x16_bf16 v[16:31], v[182:185], v[158:161], v[16:31]
	v_exp_f32_e32 v106, v106
	v_exp_f32_e32 v107, v107
	v_cvt_pk_bf16_f32 v158, v96, v97
	v_cvt_pk_bf16_f32 v159, v98, v99
	v_add_f32_e32 v141, v141, v100
	v_add_f32_e32 v150, v150, v101
	v_mfma_f32_32x32x16_bf16 v[80:95], v[178:181], v[162:165], v[80:95]
	v_exp_f32_e32 v108, v108
	v_exp_f32_e32 v109, v109
	v_cvt_pk_bf16_f32 v160, v100, v101
	v_cvt_pk_bf16_f32 v161, v102, v103
	v_add_f32_e32 v141, v141, v102
	v_add_f32_e32 v150, v150, v103
	v_mfma_f32_32x32x16_bf16 v[16:31], v[186:189], v[162:165], v[16:31]
	ds_read_b128 v[174:177], v32 offset:9216
	ds_read_b128 v[178:181], v32 offset:9248
	ds_read_b128 v[182:185], v32 offset:13824
	ds_read_b128 v[186:189], v32 offset:13856
	v_exp_f32_e32 v110, v110
	v_exp_f32_e32 v111, v111
	v_add_f32_e32 v141, v141, v104
	v_add_f32_e32 v150, v150, v105
	v_add_f32_e32 v141, v141, v106
	v_add_f32_e32 v150, v150, v107
	v_add_f32_e32 v141, v141, v108
	v_add_f32_e32 v150, v150, v109
	v_cvt_pk_bf16_f32 v162, v104, v105
	v_cvt_pk_bf16_f32 v163, v106, v107
	v_cvt_pk_bf16_f32 v164, v108, v109
	v_add_f32_e32 v141, v141, v110
	v_add_f32_e32 v150, v150, v111
	v_cvt_pk_bf16_f32 v165, v110, v111
	s_waitcnt lgkmcnt(0)
	v_mfma_f32_32x32x16_bf16 v[96:111], v[166:169], v[112:115], v[48:63]
	v_exp_f32_e32 v116, v116
	v_exp_f32_e32 v117, v117
	v_exp_f32_e32 v118, v118
	v_exp_f32_e32 v119, v119
	v_mfma_f32_32x32x16_bf16 v[96:111], v[170:173], v[42:45], v[96:111]
	v_exp_f32_e32 v120, v120
	v_exp_f32_e32 v121, v121
	v_exp_f32_e32 v122, v122
	v_exp_f32_e32 v123, v123
	ds_read_b128 v[166:169], v32 offset:4672
	ds_read_b128 v[170:173], v32 offset:4704
	v_mfma_f32_32x32x16_bf16 v[64:79], v[174:177], v[158:161], v[64:79]
	v_exp_f32_e32 v124, v124
	v_exp_f32_e32 v125, v125
	v_add_f32_e32 v140, v140, v116
	v_add_f32_e32 v151, v151, v117
	v_add_f32_e32 v140, v140, v118
	v_add_f32_e32 v151, v151, v119
	v_mfma_f32_32x32x16_bf16 v[0:15], v[182:185], v[158:161], v[0:15]
	v_exp_f32_e32 v126, v126
	v_exp_f32_e32 v127, v127
	v_cvt_pk_bf16_f32 v158, v116, v117
	v_cvt_pk_bf16_f32 v159, v118, v119
	v_add_f32_e32 v140, v140, v120
	v_add_f32_e32 v151, v151, v121
	v_mfma_f32_32x32x16_bf16 v[64:79], v[178:181], v[162:165], v[64:79]
	v_exp_f32_e32 v128, v128
	v_exp_f32_e32 v129, v129
	v_cvt_pk_bf16_f32 v160, v120, v121
	v_cvt_pk_bf16_f32 v161, v122, v123
	v_add_f32_e32 v140, v140, v122
	v_add_f32_e32 v151, v151, v123
	v_mfma_f32_32x32x16_bf16 v[0:15], v[186:189], v[162:165], v[0:15]
	v_exp_f32_e32 v130, v130
	v_exp_f32_e32 v131, v131
	v_add_f32_e32 v140, v140, v124
	v_add_f32_e32 v151, v151, v125
	v_add_f32_e32 v140, v140, v126
	v_add_f32_e32 v151, v151, v127
	v_add_f32_e32 v140, v140, v128
	v_add_f32_e32 v151, v151, v129
	v_cvt_pk_bf16_f32 v162, v124, v125
	v_cvt_pk_bf16_f32 v163, v126, v127
	v_cvt_pk_bf16_f32 v164, v128, v129
	v_add_f32_e32 v140, v140, v130
	v_add_f32_e32 v151, v151, v131
	v_cvt_pk_bf16_f32 v165, v130, v131
	s_waitcnt lgkmcnt(0)
; DI float ex2(float x) { return __builtin_amdgcn_exp2f(x); }
; template <int MODE>
; DI void attn_unit(unsigned char* lds, const AttnParams& ap, int b, int h, int qb, int tid) {
;     ...
;   for (int n = 0; n < ntiles; n += NCH) {
;     const int jb = (MODE == 2) ? jhi - n : jlo + n;
;     __syncthreads();
;     if (MODE == 2 && D_EARLY) { int alld = 1;
; #pragma unroll
;       for (int w = 0; w < 8; ++w) alld &= flags[w];
;       if (alld) break; }
; #pragma unroll
;     for (int c = 0; c < NCH; ++c) { *(u32x4*)(Ks0 + (c * 64 + lrow) * 72 + 8 * lch) = kreg[c]; *(u32x4*)(Vs0 + (c * 64 + lrow) * 72 + 8 * lch) = vreg[c]; }
;     __syncthreads();
;     if (n + NCH < ntiles) {
; #pragma unroll
;       for (int c = 0; c < NCH; ++c) { const int jn = (MODE == 2) ? jb - NCH - c : jb + NCH + c; kreg[c] = *(const u32x4*)(kg + (size_t)jn * 64 * PLD); vreg[c] = *(const u32x4*)(vg + (size_t)jn * 4096); } }
; #pragma unroll
;     for (int c = 0; c < NCH; ++c) {
;     const int j = (MODE == 2) ? jb - c : jb + c;
;     const bf16_t* Ks = Ks0 + c * 64 * 72; const bf16_t* Vs = Vs0 + c * 64 * 72;
;     const bool active = (j <= cw) && (MODE != 0 || j >= cw - 8);
;     if (!active) continue;
;     if (MODE == 2 && D_EARLY && wdone) continue;
;     if (MODE == 1) {
; #pragma unroll
;       for (int kh = 0; kh < 2; ++kh) {
;         const bf16_t* kb = Ks + (32 * kh + r32) * 72 + 8 * hi;
;         bf16x8 p0[2], p1[2];
;         { f32x16 s0 = splat16(ap.negM);
;           s0 = MFMA32(*(const bf16x8*)(kb), qf[0], s0); s0 = MFMA32(*(const bf16x8*)(kb + 16), qf[1], s0);
; #pragma unroll
;           for (int i = 0; i < 16; ++i) { s0[i] = ex2(s0[i]); l0 += s0[i]; }
;           p0[0] = pack8(s0, 0); p0[1] = pack8(s0, 1); }
;         { f32x16 s1 = splat16(ap.negM);
;           s1 = MFMA32(*(const bf16x8*)(kb + 32), qf[2], s1); s1 = MFMA32(*(const bf16x8*)(kb + 48), qf[3], s1);
; #pragma unroll
;           for (int i = 0; i < 16; ++i) { s1[i] = ex2(s1[i]); l1 += s1[i]; }
;           p1[0] = pack8(s1, 0); p1[1] = pack8(s1, 1); }
; #pragma unroll
;         for (int kk = 0; kk < 2; ++kk) {
; #pragma unroll
;           for (int eb = 0; eb < 2; ++eb) { const bf16_t* vb = Vs + (32 * eb + r32) * 72 + 32 * kh + 16 * kk + 8 * hi; const bf16x8 vf = *(const bf16x8*)vb;
;             O0[eb] = MFMA32(vf, p0[kk], O0[eb]); O1[eb] = MFMA32(vf, p1[kk], O1[eb]); } }
;       }
	v_mfma_f32_32x32x16_bf16 v[116:131], v[166:169], v[38:41], v[48:63]
	v_exp_f32_e32 v96, v96
	v_exp_f32_e32 v97, v97
	v_exp_f32_e32 v98, v98
	v_exp_f32_e32 v99, v99
	v_mfma_f32_32x32x16_bf16 v[116:131], v[170:173], v[34:37], v[116:131]
	v_exp_f32_e32 v100, v100
	v_exp_f32_e32 v101, v101
	v_exp_f32_e32 v102, v102
	v_exp_f32_e32 v103, v103
	ds_read_b128 v[166:169], v157
	ds_read_b128 v[170:173], v157 offset:32
	v_mfma_f32_32x32x16_bf16 v[80:95], v[174:177], v[158:161], v[80:95]
	v_exp_f32_e32 v104, v104
	v_exp_f32_e32 v105, v105
	v_add_f32_e32 v141, v141, v96
	v_add_f32_e32 v150, v150, v97
	v_add_f32_e32 v141, v141, v98
	v_add_f32_e32 v150, v150, v99
	v_mfma_f32_32x32x16_bf16 v[16:31], v[182:185], v[158:161], v[16:31]
	v_exp_f32_e32 v106, v106
	v_exp_f32_e32 v107, v107
	v_cvt_pk_bf16_f32 v158, v96, v97
	v_cvt_pk_bf16_f32 v159, v98, v99
	v_add_f32_e32 v141, v141, v100
	v_add_f32_e32 v150, v150, v101
	v_mfma_f32_32x32x16_bf16 v[80:95], v[178:181], v[162:165], v[80:95]
	v_exp_f32_e32 v108, v108
	v_exp_f32_e32 v109, v109
	v_cvt_pk_bf16_f32 v160, v100, v101
	v_cvt_pk_bf16_f32 v161, v102, v103
	v_add_f32_e32 v141, v141, v102
	v_add_f32_e32 v150, v150, v103
	v_mfma_f32_32x32x16_bf16 v[16:31], v[186:189], v[162:165], v[16:31]
	ds_read_b128 v[174:177], v32 offset:9280
	ds_read_b128 v[178:181], v32 offset:9312
	ds_read_b128 v[182:185], v32 offset:13888
	ds_read_b128 v[186:189], v32 offset:13920
	v_exp_f32_e32 v110, v110
	v_exp_f32_e32 v111, v111
	v_add_f32_e32 v141, v141, v104
	v_add_f32_e32 v150, v150, v105
	v_add_f32_e32 v141, v141, v106
	v_add_f32_e32 v150, v150, v107
	v_add_f32_e32 v141, v141, v108
	v_add_f32_e32 v150, v150, v109
	v_cvt_pk_bf16_f32 v162, v104, v105
	v_cvt_pk_bf16_f32 v163, v106, v107
	v_cvt_pk_bf16_f32 v164, v108, v109
	v_add_f32_e32 v141, v141, v110
	v_add_f32_e32 v150, v150, v111
	v_cvt_pk_bf16_f32 v165, v110, v111
	s_waitcnt lgkmcnt(0)
	v_mfma_f32_32x32x16_bf16 v[96:111], v[166:169], v[112:115], v[48:63]
	v_exp_f32_e32 v116, v116
	v_exp_f32_e32 v117, v117
	v_exp_f32_e32 v118, v118
	v_exp_f32_e32 v119, v119
	v_mfma_f32_32x32x16_bf16 v[96:111], v[170:173], v[42:45], v[96:111]
	v_exp_f32_e32 v120, v120
	v_exp_f32_e32 v121, v121
	v_exp_f32_e32 v122, v122
	v_exp_f32_e32 v123, v123
	ds_read_b128 v[166:169], v157 offset:64
	ds_read_b128 v[170:173], v157 offset:96
	v_mfma_f32_32x32x16_bf16 v[64:79], v[174:177], v[158:161], v[64:79]
	v_exp_f32_e32 v124, v124
	v_exp_f32_e32 v125, v125
	v_add_f32_e32 v140, v140, v116
	v_add_f32_e32 v151, v151, v117
	v_add_f32_e32 v140, v140, v118
	v_add_f32_e32 v151, v151, v119
	v_mfma_f32_32x32x16_bf16 v[0:15], v[182:185], v[158:161], v[0:15]
	v_exp_f32_e32 v126, v126
	v_exp_f32_e32 v127, v127
	v_cvt_pk_bf16_f32 v158, v116, v117
	v_cvt_pk_bf16_f32 v159, v118, v119
	v_add_f32_e32 v140, v140, v120
	v_add_f32_e32 v151, v151, v121
	v_mfma_f32_32x32x16_bf16 v[64:79], v[178:181], v[162:165], v[64:79]
	v_exp_f32_e32 v128, v128
	v_exp_f32_e32 v129, v129
	v_cvt_pk_bf16_f32 v160, v120, v121
	v_cvt_pk_bf16_f32 v161, v122, v123
	v_add_f32_e32 v140, v140, v122
	v_add_f32_e32 v151, v151, v123
	v_mfma_f32_32x32x16_bf16 v[0:15], v[186:189], v[162:165], v[0:15]
	v_exp_f32_e32 v130, v130
	v_exp_f32_e32 v131, v131
	v_add_f32_e32 v140, v140, v124
	v_add_f32_e32 v151, v151, v125
	v_add_f32_e32 v140, v140, v126
	v_add_f32_e32 v151, v151, v127
	v_add_f32_e32 v140, v140, v128
	v_add_f32_e32 v151, v151, v129
	v_cvt_pk_bf16_f32 v162, v124, v125
	v_cvt_pk_bf16_f32 v163, v126, v127
	v_cvt_pk_bf16_f32 v164, v128, v129
	v_add_f32_e32 v140, v140, v130
	v_add_f32_e32 v151, v151, v131
	v_cvt_pk_bf16_f32 v165, v130, v131
	s_waitcnt vmcnt(0)
	ds_write_b128 v146, v[204:207]
	ds_write_b128 v146, v[142:145] offset:9216
	s_mov_b32 s0, s9
	s_mov_b32 s9, s10
	s_mov_b32 s10, s11
	s_mov_b32 s11, s0
	v_mov_b32_e32 v32, v157
	v_add_u32_e32 v157, s10, v133
	v_add_u32_e32 v146, s11, v190
	s_add_i32 s4, s4, 1
	s_waitcnt lgkmcnt(0)
	s_barrier
	s_nop 0
	s_barrier
	s_cmp_le_u32 s4, s5
	s_cbranch_scc1 .Lc_tile_loop
	v_mfma_f32_32x32x16_bf16 v[80:95], v[174:177], v[158:161], v[80:95]
	v_mfma_f32_32x32x16_bf16 v[16:31], v[182:185], v[158:161], v[16:31]
	v_mfma_f32_32x32x16_bf16 v[80:95], v[178:181], v[162:165], v[80:95]
	v_mfma_f32_32x32x16_bf16 v[16:31], v[186:189], v[162:165], v[16:31]
	s_cmp_gt_u32 s4, s8
	s_cbranch_scc1 .Lc_tiles_done
.Lc_idle_loop:
	global_load_dwordx4 v[204:207], v[138:139], off
	global_load_dwordx4 v[142:145], v[136:137], off
	v_lshl_add_u64 v[138:139], v[138:139], 0, s[2:3]
	v_lshl_add_u64 v[136:137], v[136:137], 0, s[18:19]
	s_waitcnt vmcnt(0)
	ds_write_b128 v146, v[204:207]
	ds_write_b128 v146, v[142:145] offset:9216
	s_mov_b32 s0, s9
	s_mov_b32 s9, s10
	s_mov_b32 s10, s11
	s_mov_b32 s11, s0
	v_add_u32_e32 v146, s11, v190
	s_add_i32 s4, s4, 1
	s_waitcnt lgkmcnt(0)
	s_barrier
	s_nop 0
	s_barrier
	s_cmp_le_u32 s4, s8
	s_cbranch_scc1 .Lc_idle_loop
